# q/k/u projection rstd table: all units' statistic loads issued before the first wait
# baseline (speedup 1.0000x reference)
; #define LAS __attribute__((address_space(3)))
; __device__ __forceinline__ float fx_get(const i64* p) { return (float)(*p) * FXI; }
;     __host__ __device__ bool next(int i, Unit& u) const {
;         const long L = (long)i * G + c; if (L >= nwg) return false;
;         int wgid = (int)L; { constexpr int q = nwg / NXCD, r = nwg % NXCD; const int xcd = wgid % NXCD, off = wgid / NXCD; wgid = (xcd < r ? xcd * (q + 1) : r * (q + 1) + (xcd - r) * q) + off; }
;         const int gid = wgid / nig, fm = gid * WGM, w = wgid % nig;
;         u.pm = fm + (w % gsz); u.pn = w / gsz; return true;
; template <bool BY_COL, class Sched> __device__ __forceinline__ void stage_rstd(LAS unsigned char* lds, const Sched& S, const i64* ssq) {
;     LAS float* rsl = (LAS float*)(lds + RSL_OFF); const int tid = threadIdx.x;
; #pragma unroll 1
;     for (int i = 0; i < RSL_UNITS; ++i) { Unit u; if (!S.next(i, u)) break;
;         if (tid < 256) rsl[i * 256 + tid] = __builtin_amdgcn_rsqf(fx_get(ssq + (BY_COL ? u.pn : u.pm) * 256 + tid) * (1.0f / DM) + EPS); }
;     __syncthreads();
.LBB0_588:
	s_mov_b64 s[4:5], -1
	v_writelane_b32 v252, s4, 23
	s_andn2_b64 vcc, exec, s[28:29]
	s_mov_b64 s[28:29], -1
	v_writelane_b32 v252, s5, 24
	s_cbranch_vccnz .LBB0_196
	v_readlane_b32 s4, v254, 50
	v_readlane_b32 s5, v254, 51
	s_andn2_b64 vcc, exec, s[4:5]
	s_cbranch_vccnz .LBB0_1077
	v_readlane_b32 s4, v252, 51
	v_readlane_b32 s5, v252, 52
	s_waitcnt lgkmcnt(0)
	s_mov_b64 s[28:29], s[94:95]
	s_lshl_b64 s[90:91], s[4:5], 3
	s_add_u32 s4, s28, s90
	s_addc_u32 s5, s29, s91
	v_mov_b32_e32 v215, v1
	s_waitcnt lgkmcnt(0)
	v_lshl_add_u64 v[2:3], s[4:5], 0, v[214:215]
	s_mov_b64 s[4:5], 0x20000
	v_lshl_add_u64 v[2:3], v[2:3], 0, s[4:5]
	s_movk_i32 s4, 0xe800
	s_mov_b64 s[30:31], s[2:3]
	s_and_saveexec_b64 s[42:43], s[38:39]
	s_mov_b32 s4, 0
	v_cmp_gt_i64_e32 vcc, s[30:31], v[222:223]
	s_cbranch_vccnz .Lrq_issued
	s_ashr_i32 s5, s30, 31
	s_lshr_b32 s5, s5, 29
	s_add_i32 s5, s30, s5
	s_ashr_i32 s6, s5, 3
	s_and_b32 s5, s5, -8
	s_sub_i32 s5, s30, s5
	s_cmp_lt_i32 s5, 0
	s_cselect_b32 s7, 49, 48
	s_mul_i32 s5, s7, s5
	s_add_i32 s5, s5, s6
	s_mul_hi_i32 s6, s5, 0x2aaaaaab
	s_lshr_b32 s7, s6, 31
	s_ashr_i32 s6, s6, 3
	s_add_i32 s6, s6, s7
	s_mul_i32 s7, s6, 48
	s_sub_i32 s5, s5, s7
	s_bfe_i32 s7, s5, 0x80000
	s_bfe_u32 s7, s7, 0x3000c
	s_add_i32 s7, s5, s7
	s_and_b32 s7, s7, 0xf8
	s_sub_i32 s5, s5, s7
	s_sext_i32_i8 s5, s5
	s_lshl_b32 s6, s6, 11
	s_lshl_b32 s5, s5, 8
	s_add_i32 s6, s5, s6
	s_ashr_i32 s7, s6, 31
	v_lshl_add_u64 v[4:5], s[6:7], 3, v[2:3]
	global_load_dwordx2 v[4:5], v[4:5], off
	s_add_i32 s4, s4, 1
	s_add_u32 s30, s30, s70
	s_addc_u32 s31, s31, s61
	v_cmp_gt_i64_e32 vcc, s[30:31], v[222:223]
	s_cbranch_vccnz .Lrq_issued
	s_ashr_i32 s5, s30, 31
	s_lshr_b32 s5, s5, 29
	s_add_i32 s5, s30, s5
	s_ashr_i32 s6, s5, 3
	s_and_b32 s5, s5, -8
	s_sub_i32 s5, s30, s5
	s_cmp_lt_i32 s5, 0
	s_cselect_b32 s7, 49, 48
	s_mul_i32 s5, s7, s5
	s_add_i32 s5, s5, s6
	s_mul_hi_i32 s6, s5, 0x2aaaaaab
	s_lshr_b32 s7, s6, 31
	s_ashr_i32 s6, s6, 3
	s_add_i32 s6, s6, s7
	s_mul_i32 s7, s6, 48
	s_sub_i32 s5, s5, s7
	s_bfe_i32 s7, s5, 0x80000
	s_bfe_u32 s7, s7, 0x3000c
	s_add_i32 s7, s5, s7
	s_and_b32 s7, s7, 0xf8
	s_sub_i32 s5, s5, s7
	s_sext_i32_i8 s5, s5
	s_lshl_b32 s6, s6, 11
	s_lshl_b32 s5, s5, 8
	s_add_i32 s6, s5, s6
	s_ashr_i32 s7, s6, 31
	v_lshl_add_u64 v[6:7], s[6:7], 3, v[2:3]
	global_load_dwordx2 v[6:7], v[6:7], off
	s_add_i32 s4, s4, 1
	s_add_u32 s30, s30, s70
	s_addc_u32 s31, s31, s61
	v_cmp_gt_i64_e32 vcc, s[30:31], v[222:223]
	s_cbranch_vccnz .Lrq_issued
	s_ashr_i32 s5, s30, 31
	s_lshr_b32 s5, s5, 29
	s_add_i32 s5, s30, s5
	s_ashr_i32 s6, s5, 3
	s_and_b32 s5, s5, -8
	s_sub_i32 s5, s30, s5
	s_cmp_lt_i32 s5, 0
	s_cselect_b32 s7, 49, 48
	s_mul_i32 s5, s7, s5
	s_add_i32 s5, s5, s6
	s_mul_hi_i32 s6, s5, 0x2aaaaaab
	s_lshr_b32 s7, s6, 31
	s_ashr_i32 s6, s6, 3
	s_add_i32 s6, s6, s7
	s_mul_i32 s7, s6, 48
	s_sub_i32 s5, s5, s7
	s_bfe_i32 s7, s5, 0x80000
	s_bfe_u32 s7, s7, 0x3000c
	s_add_i32 s7, s5, s7
	s_and_b32 s7, s7, 0xf8
	s_sub_i32 s5, s5, s7
	s_sext_i32_i8 s5, s5
	s_lshl_b32 s6, s6, 11
	s_lshl_b32 s5, s5, 8
	s_add_i32 s6, s5, s6
	s_ashr_i32 s7, s6, 31
	v_lshl_add_u64 v[8:9], s[6:7], 3, v[2:3]
	global_load_dwordx2 v[8:9], v[8:9], off
	s_add_i32 s4, s4, 1
	s_add_u32 s30, s30, s70
	s_addc_u32 s31, s31, s61
	v_cmp_gt_i64_e32 vcc, s[30:31], v[222:223]
	s_cbranch_vccnz .Lrq_issued
	s_ashr_i32 s5, s30, 31
	s_lshr_b32 s5, s5, 29
	s_add_i32 s5, s30, s5
	s_ashr_i32 s6, s5, 3
	s_and_b32 s5, s5, -8
	s_sub_i32 s5, s30, s5
	s_cmp_lt_i32 s5, 0
	s_cselect_b32 s7, 49, 48
	s_mul_i32 s5, s7, s5
	s_add_i32 s5, s5, s6
	s_mul_hi_i32 s6, s5, 0x2aaaaaab
	s_lshr_b32 s7, s6, 31
	s_ashr_i32 s6, s6, 3
	s_add_i32 s6, s6, s7
	s_mul_i32 s7, s6, 48
	s_sub_i32 s5, s5, s7
	s_bfe_i32 s7, s5, 0x80000
	s_bfe_u32 s7, s7, 0x3000c
	s_add_i32 s7, s5, s7
	s_and_b32 s7, s7, 0xf8
	s_sub_i32 s5, s5, s7
	s_sext_i32_i8 s5, s5
	s_lshl_b32 s6, s6, 11
	s_lshl_b32 s5, s5, 8
	s_add_i32 s6, s5, s6
	s_ashr_i32 s7, s6, 31
	v_lshl_add_u64 v[10:11], s[6:7], 3, v[2:3]
	global_load_dwordx2 v[10:11], v[10:11], off
	s_add_i32 s4, s4, 1
	s_add_u32 s30, s30, s70
	s_addc_u32 s31, s31, s61
	v_cmp_gt_i64_e32 vcc, s[30:31], v[222:223]
	s_cbranch_vccnz .Lrq_issued
	s_ashr_i32 s5, s30, 31
	s_lshr_b32 s5, s5, 29
	s_add_i32 s5, s30, s5
	s_ashr_i32 s6, s5, 3
	s_and_b32 s5, s5, -8
	s_sub_i32 s5, s30, s5
	s_cmp_lt_i32 s5, 0
	s_cselect_b32 s7, 49, 48
	s_mul_i32 s5, s7, s5
	s_add_i32 s5, s5, s6
	s_mul_hi_i32 s6, s5, 0x2aaaaaab
	s_lshr_b32 s7, s6, 31
	s_ashr_i32 s6, s6, 3
	s_add_i32 s6, s6, s7
	s_mul_i32 s7, s6, 48
	s_sub_i32 s5, s5, s7
	s_bfe_i32 s7, s5, 0x80000
	s_bfe_u32 s7, s7, 0x3000c
	s_add_i32 s7, s5, s7
	s_and_b32 s7, s7, 0xf8
	s_sub_i32 s5, s5, s7
	s_sext_i32_i8 s5, s5
	s_lshl_b32 s6, s6, 11
	s_lshl_b32 s5, s5, 8
	s_add_i32 s6, s5, s6
	s_ashr_i32 s7, s6, 31
	v_lshl_add_u64 v[12:13], s[6:7], 3, v[2:3]
	global_load_dwordx2 v[12:13], v[12:13], off
	s_add_i32 s4, s4, 1
	s_add_u32 s30, s30, s70
	s_addc_u32 s31, s31, s61
	v_cmp_gt_i64_e32 vcc, s[30:31], v[222:223]
	s_cbranch_vccnz .Lrq_issued
	s_ashr_i32 s5, s30, 31
	s_lshr_b32 s5, s5, 29
	s_add_i32 s5, s30, s5
	s_ashr_i32 s6, s5, 3
	s_and_b32 s5, s5, -8
	s_sub_i32 s5, s30, s5
	s_cmp_lt_i32 s5, 0
	s_cselect_b32 s7, 49, 48
	s_mul_i32 s5, s7, s5
	s_add_i32 s5, s5, s6
	s_mul_hi_i32 s6, s5, 0x2aaaaaab
	s_lshr_b32 s7, s6, 31
	s_ashr_i32 s6, s6, 3
	s_add_i32 s6, s6, s7
	s_mul_i32 s7, s6, 48
	s_sub_i32 s5, s5, s7
	s_bfe_i32 s7, s5, 0x80000
	s_bfe_u32 s7, s7, 0x3000c
	s_add_i32 s7, s5, s7
	s_and_b32 s7, s7, 0xf8
	s_sub_i32 s5, s5, s7
	s_sext_i32_i8 s5, s5
	s_lshl_b32 s6, s6, 11
	s_lshl_b32 s5, s5, 8
	s_add_i32 s6, s5, s6
	s_ashr_i32 s7, s6, 31
	v_lshl_add_u64 v[14:15], s[6:7], 3, v[2:3]
	global_load_dwordx2 v[14:15], v[14:15], off
	s_add_i32 s4, s4, 1

; #define PG8_LAS __attribute__((address_space(3)))
; #define PG8_STAGE(bufoff, gbase, voff) do { _Pragma("unroll") for (int _i = 0; _i < 2; ++_i) \
;         __builtin_amdgcn_global_load_lds((const unsigned*)((const char*)(gbase) + (voff)[_i]), (PG8_LAS unsigned*)(lds + (bufoff) + ldsw + _i * 8192), 16, 0, 0); } while (0)
; #define PG8_WAIT_V(n) asm volatile("s_waitcnt vmcnt(" #n ")" ::: "memory")
; template <class Epi, class Sched, bool ALIGN_EPI = false>
; __device__ __forceinline__ void gemm_phase(PG8_LAS unsigned char* lds, const Gemm g, const Sched& S, const Epi& E) {
;     int tid_ = threadIdx.x; asm volatile("" : "+v"(tid_));
;     const int tid = tid_, wid = __builtin_amdgcn_readfirstlane(tid >> 6), lane = tid & 63, wr = wid >> 2, wc = wid & 3, fr = lane & 15, fq = lane >> 4;
;     const int K = g.K, nt = K / BK;
;     unsigned voffA[2], voffB[2];
; #pragma unroll
;     for (int i = 0; i < 2; ++i) { int R, C; stage_rc(tid * 16 + i * 8192, R, C); const int Rb = Epi::PERM ? ((R & ~31) + perm32(R & 31)) : R;
;         voffA[i] = (unsigned)(R * K + C) * 2u; voffB[i] = (unsigned)(Rb * K + C) * 2u; }
;     const size_t kstep = (size_t)(BK * 2);
;     const size_t hstep = (size_t)HALF * K * 2;
;     const size_t tstep = 2 * hstep;
;     const unsigned ldsw = (unsigned)wid * 1024u;
;     const int aoff = lds_byte(wr * 64 + fr, fq * 8), boff = lds_byte(wc * 32 + fr, fq * 8);
;     ...
;     Unit cur, nxt; int ui = 0;
;     if (!S.next(0, cur)) return;
;     f32x4 acc[2][2][4][2];
; #pragma unroll
;     for (int a = 0; a < 2; ++a)
; #pragma unroll
;         for (int b = 0; b < 2; ++b)
; #pragma unroll
;             for (int m = 0; m < 4; ++m)
; #pragma unroll
;                 for (int n = 0; n < 2; ++n) acc[a][b][m][n] = (f32x4){0.f, 0.f, 0.f, 0.f};
;     bf16x8 At[4][2], B0[2][2], B1[2][2];
;     const char* cA = (const char*)g.A + (size_t)cur.pm * tstep; const char* cB = (const char*)g.Bt + (size_t)cur.pn * tstep;
;     {
;         PG8_STAGE(PG8_SB(0, 0), cB, voffB); PG8_STAGE(PG8_SB(0, 1), cB + hstep, voffB); PG8_STAGE(PG8_SA(0, 0), cA, voffA); PG8_STAGE(PG8_SA(0, 1), cA + hstep, voffA);
;         if (wr == 1) PG8_BAR;
;         PG8_WAIT_V(2); PG8_BAR;
;         PG8_STAGE(PG8_SB(1, 0), cB + kstep, voffB); PG8_STAGE(PG8_SA(1, 0), cA + kstep, voffA); PG8_STAGE(PG8_SB(1, 1), cB + hstep + kstep, voffB);
;         PG8_WAIT_V(6); PG8_BAR;
;     }
.Lrq_done:
	s_or_b64 exec, exec, s[42:43]
.LBB0_596:
	v_readlane_b32 s4, v253, 50
	v_mov_b32_e32 v15, v210
	v_readlane_b32 s5, v253, 51
	s_waitcnt vmcnt(0) lgkmcnt(0)
	s_barrier
	s_andn2_b64 vcc, exec, s[4:5]
	v_readfirstlane_b32 s5, v15
	s_cbranch_vccnz .LBB0_820
	v_lshlrev_b32_e32 v2, 4, v15
	v_add_u32_e32 v3, 0x2000, v2
	v_ashrrev_i32_e32 v0, 31, v3
	v_lshrrev_b32_e32 v0, 22, v0
	v_add_u32_e32 v0, v3, v0
	v_ashrrev_i32_e32 v0, 10, v0
	v_mul_i32_i24_e32 v4, 0x400, v0
	v_sub_u32_e32 v3, v3, v4
	v_lshrrev_b32_e32 v4, 4, v3
	v_bitop3_b32 v3, v4, v3, 32 bitop3:0x6c
	v_ashrrev_i32_e32 v4, 31, v3
	v_lshrrev_b32_e32 v4, 26, v4
	v_add_u32_e32 v4, v3, v4
	v_lshlrev_b32_e32 v5, 3, v0
	v_ashrrev_i32_e32 v10, 6, v4
	v_and_b32_e32 v5, -16, v5
	v_add_u32_e32 v5, v10, v5
	v_and_b32_e32 v6, 3, v10
	s_mov_b32 s8, 0x1fffe0
	v_lshrrev_b32_e32 v7, 2, v5
	v_lshlrev_b32_e32 v8, 1, v5
	v_and_or_b32 v6, v5, s8, v6
	v_and_b32_e32 v7, 4, v7
	v_and_b32_e32 v8, 24, v8
	v_and_b32_e32 v4, 0xc0, v4
	v_or3_b32 v6, v6, v7, v8
	v_sub_u32_e32 v3, v3, v4
	v_mov_b32_e32 v8, 1
	v_lshlrev_b32_e32 v7, 5, v0
	v_ashrrev_i16_sdwa v3, v8, sext(v3) dst_sel:DWORD dst_unused:UNUSED_PAD src0_sel:DWORD src1_sel:BYTE_0
	v_and_b32_e32 v7, 32, v7
	v_bfe_i32 v11, v3, 0, 16
	v_add_lshl_u32 v3, v7, v11, 1
	v_lshl_add_u32 v154, v6, 11, v3
	v_lshl_add_u32 v156, v5, 11, v3
	v_bfe_i32 v3, v15, 27, 1
	v_lshrrev_b32_e32 v3, 22, v3
	v_add_u32_e32 v3, v2, v3
	v_and_b32_e32 v3, 0xfffffc00, v3
	v_sub_u32_e32 v2, v2, v3
	v_lshrrev_b32_e32 v3, 4, v2
	v_ashrrev_i32_e32 v4, 31, v15
	v_bitop3_b32 v2, v3, v2, 32 bitop3:0x6c
	v_lshrrev_b32_e32 v4, 26, v4
	s_ashr_i32 s14, s5, 6
	v_ashrrev_i32_e32 v3, 31, v2
	v_add_u32_e32 v4, v15, v4
	s_ashr_i32 s4, s5, 8
	s_lshl_b32 s36, s14, 10
	v_readlane_b32 s6, v254, 40
	v_lshrrev_b32_e32 v3, 26, v3
	v_ashrrev_i32_e32 v13, 6, v4
	s_add_u32 s6, s28, s6
	v_add_u32_e32 v3, v2, v3
	v_lshlrev_b32_e32 v4, 3, v13
	s_addc_u32 s7, s29, 0
	v_ashrrev_i32_e32 v12, 6, v3
	v_and_b32_e32 v4, -16, v4
	s_add_u32 s96, s28, 0xa400000
	v_add_u32_e32 v4, v12, v4
	s_addc_u32 s97, s29, 0
	v_and_b32_e32 v5, 3, v12
	v_lshrrev_b32_e32 v6, 2, v4
	v_lshlrev_b32_e32 v7, 1, v4
	v_and_b32_e32 v3, 0xc0, v3
	s_add_u32 s6, s6, 0x1480000
	v_and_or_b32 v5, v4, s8, v5
	v_and_b32_e32 v6, 4, v6
	v_and_b32_e32 v7, 24, v7
	v_sub_u32_e32 v2, v2, v3
	s_addc_u32 s7, s7, 0
	v_or3_b32 v5, v5, v6, v7
	v_lshlrev_b32_e32 v6, 5, v13
	v_ashrrev_i16_sdwa v2, v8, sext(v2) dst_sel:DWORD dst_unused:UNUSED_PAD src0_sel:DWORD src1_sel:BYTE_0
	v_readlane_b32 s8, v253, 56
	v_and_b32_e32 v6, 32, v6
	v_bfe_i32 v14, v2, 0, 16
	v_readlane_b32 s9, v253, 57
	s_add_u32 s50, s6, s8
	v_add_lshl_u32 v2, v6, v14, 1
	s_addc_u32 s51, s7, s9
	s_add_i32 s8, s36, 0
	v_lshl_add_u32 v158, v5, 11, v2
	s_add_i32 m0, s8, 0x10000
	v_lshl_add_u32 v160, v4, 11, v2
	global_load_lds_dwordx4 v158, s[50:51]
	s_add_i32 m0, s8, 0x12000
	s_add_u32 s10, s50, 0x40000
	global_load_lds_dwordx4 v154, s[50:51]
	s_addc_u32 s11, s51, 0
	s_add_i32 m0, s8, 0x14000
	v_mov_b32_e32 v159, v1
	global_load_lds_dwordx4 v158, s[10:11]
	s_add_i32 m0, s8, 0x16000
	v_mov_b32_e32 v155, v1
	global_load_lds_dwordx4 v154, s[10:11]
	v_readlane_b32 s10, v254, 13
	v_readlane_b32 s11, v254, 14
	s_add_u32 s48, s96, s10
	s_addc_u32 s49, s97, s11
	s_add_i32 s9, s8, 0x2000
	s_mov_b32 m0, s8
	s_add_u32 s12, s48, 0x40000
	global_load_lds_dwordx4 v160, s[48:49]
	s_mov_b32 m0, s9
	s_addc_u32 s13, s49, 0
	s_add_i32 s10, s8, 0x4000
	global_load_lds_dwordx4 v156, s[48:49]
	s_mov_b32 m0, s10
	s_add_i32 s11, s8, 0x6000
	global_load_lds_dwordx4 v160, s[12:13]
	s_mov_b32 m0, s11
	v_mov_b32_e32 v161, v1
	global_load_lds_dwordx4 v156, s[12:13]
	v_mov_b32_e32 v157, v1
	s_cmp_eq_u32 s4, 1
	v_mov_b32_e32 v251, 1
	v_lshl_add_u64 v[8:9], s[50:51], 0, v[158:159]
	v_lshl_add_u64 v[6:7], s[50:51], 0, v[154:155]
	v_lshl_add_u64 v[2:3], s[48:49], 0, v[160:161]
	s_cselect_b64 s[80:81], -1, 0
	s_cmp_lg_u32 s4, 1
	v_lshl_add_u64 v[4:5], s[48:49], 0, v[156:157]
	s_cbranch_scc1 .LBB0_599
	s_barrier
